# seams: acquire-side buffer_inv sc1 issued at arrival (overlaps the arrive atomic round trip) instead of after the release is observed
# speedup vs baseline: 1.0343x; 1.0343x over previous
; __device__ __forceinline__ unsigned xb_ld(unsigned* p)              { return __hip_atomic_load(p, __ATOMIC_RELAXED, __HIP_MEMORY_SCOPE_AGENT); }
; __device__ __forceinline__ unsigned xb_add(unsigned* p, unsigned v) { return __hip_atomic_fetch_add(p, v, __ATOMIC_RELAXED, __HIP_MEMORY_SCOPE_AGENT); }
; #define XB_SPIN(cond, bar) do { unsigned _sp = 0; while (cond) { __builtin_amdgcn_s_sleep(1); \
;     if ((++_sp & 255u) == 0u) { if (xb_ld(&(bar)[XB_TMO])) break; if (_sp > XB_SPIN_CAP) { atomicAdd(&(bar)[XB_TMO], 1u); break; } } } } while (0)
; __device__ __forceinline__ void xcd_barrier(const XcdBarrier& b) {
;     ...
;         const unsigned old = xb_add(&bar[XB_XSUB(b.x)], 1u);
;         const unsigned gen = old / nloc;
;         if (old + 1u == (gen + 1u) * nloc) {
;             __builtin_amdgcn_fence(__ATOMIC_RELEASE, "agent");
;             asm volatile("s_waitcnt vmcnt(0)" ::: "memory");
;             const unsigned og = xb_add(&bar[XB_TOP], 1u);
;             const unsigned tg = og / nx;
;             if (og + 1u == (tg + 1u) * nx) xb_add(&bar[XB_TOPGEN], 1u);
;             else XB_SPIN(xb_ld(&bar[XB_TOPGEN]) == tg, bar);
;             __builtin_amdgcn_fence(__ATOMIC_ACQUIRE, "agent");
;             asm volatile("s_waitcnt vmcnt(0)" ::: "memory");
;         } else {
;             XB_SPIN(xb_ld(&bar[XB_TOPGEN]) == gen, bar);
.LBB0_45:
	s_or_b64 exec, exec, s[6:7]
	buffer_inv sc1
	v_cvt_f32_u32_e32 v5, v3
	s_waitcnt vmcnt(0)
	v_readfirstlane_b32 s8, v4
	s_add_u32 s6, s86, 0x3500
	s_addc_u32 s7, s87, 0
	v_rcp_iflag_f32_e32 v5, v5
	v_add_u32_e32 v6, s8, v2
	v_mul_f32_e32 v4, 0x4f7ffffe, v5
	v_cvt_u32_f32_e32 v4, v4
	v_sub_u32_e32 v5, 0, v3
	v_mul_lo_u32 v2, v5, v4
	v_mul_hi_u32 v2, v4, v2
	v_add_u32_e32 v2, v4, v2
	v_mul_hi_u32 v2, v6, v2
	v_mul_lo_u32 v4, v2, v3
	v_sub_u32_e32 v4, v6, v4
	v_add_u32_e32 v5, 1, v2
	v_cmp_ge_u32_e32 vcc, v4, v3
	s_nop 1
	v_cndmask_b32_e32 v2, v2, v5, vcc
	v_sub_u32_e32 v5, v4, v3
	v_cndmask_b32_e32 v4, v4, v5, vcc
	v_add_u32_e32 v5, 1, v2
	v_cmp_ge_u32_e32 vcc, v4, v3
	v_add_u32_e32 v4, 1, v6
	s_nop 0
	v_cndmask_b32_e32 v2, v2, v5, vcc
	v_mul_lo_u32 v5, v3, v2
	v_add_u32_e32 v3, v5, v3
	v_cmp_ne_u32_e32 vcc, v4, v3
	s_and_saveexec_b64 s[8:9], vcc
	s_xor_b64 s[8:9], exec, s[8:9]
	s_cbranch_execz .LBB0_59
	s_waitcnt lgkmcnt(0)
	v_mov_b32_e32 v1, 0
	global_load_dword v3, v1, s[6:7] sc1
	s_waitcnt vmcnt(0)
	v_cmp_eq_u32_e32 vcc, v3, v2
	s_and_saveexec_b64 s[10:11], vcc
	s_cbranch_execz .LBB0_58
	s_mov_b32 s22, 1
	s_mov_b64 s[12:13], 0
	s_branch .LBB0_49

; __device__ __forceinline__ unsigned xb_ld(unsigned* p)              { return __hip_atomic_load(p, __ATOMIC_RELAXED, __HIP_MEMORY_SCOPE_AGENT); }
; #define XB_SPIN(cond, bar) do { unsigned _sp = 0; while (cond) { __builtin_amdgcn_s_sleep(1); \
;     if ((++_sp & 255u) == 0u) { if (xb_ld(&(bar)[XB_TMO])) break; if (_sp > XB_SPIN_CAP) { atomicAdd(&(bar)[XB_TMO], 1u); break; } } } } while (0)
; __device__ __forceinline__ void xcd_barrier(const XcdBarrier& b) {
;     ...
;             XB_SPIN(xb_ld(&bar[XB_TOPGEN]) == gen, bar);
;             __builtin_amdgcn_fence(__ATOMIC_ACQUIRE, "agent");
;             asm volatile("s_waitcnt vmcnt(0)" ::: "memory");
.LBB0_58:
	s_or_b64 exec, exec, s[10:11]
	s_waitcnt vmcnt(0)
	s_waitcnt vmcnt(0)

; __device__ __forceinline__ unsigned xb_ld(unsigned* p)              { return __hip_atomic_load(p, __ATOMIC_RELAXED, __HIP_MEMORY_SCOPE_AGENT); }
; #define XB_SPIN(cond, bar) do { unsigned _sp = 0; while (cond) { __builtin_amdgcn_s_sleep(1); \
;     if ((++_sp & 255u) == 0u) { if (xb_ld(&(bar)[XB_TMO])) break; if (_sp > XB_SPIN_CAP) { atomicAdd(&(bar)[XB_TMO], 1u); break; } } } } while (0)
; __device__ __forceinline__ void xcd_barrier(const XcdBarrier& b) {
;     ...
;             else XB_SPIN(xb_ld(&bar[XB_TOPGEN]) == tg, bar);
;             __builtin_amdgcn_fence(__ATOMIC_ACQUIRE, "agent");
;             asm volatile("s_waitcnt vmcnt(0)" ::: "memory");
.LBB0_76:
	s_or_b64 exec, exec, s[4:5]
	s_waitcnt vmcnt(0)
	s_waitcnt vmcnt(0)

; __device__ __forceinline__ unsigned xb_ld(unsigned* p)              { return __hip_atomic_load(p, __ATOMIC_RELAXED, __HIP_MEMORY_SCOPE_AGENT); }
; __device__ __forceinline__ unsigned xb_add(unsigned* p, unsigned v) { return __hip_atomic_fetch_add(p, v, __ATOMIC_RELAXED, __HIP_MEMORY_SCOPE_AGENT); }
; #define XB_SPIN(cond, bar) do { unsigned _sp = 0; while (cond) { __builtin_amdgcn_s_sleep(1); \
;     if ((++_sp & 255u) == 0u) { if (xb_ld(&(bar)[XB_TMO])) break; if (_sp > XB_SPIN_CAP) { atomicAdd(&(bar)[XB_TMO], 1u); break; } } } } while (0)
; __device__ __forceinline__ void xcd_barrier(const XcdBarrier& b) {
;     ...
;         const unsigned old = xb_add(&bar[XB_XSUB(b.x)], 1u);
;         const unsigned gen = old / nloc;
;         if (old + 1u == (gen + 1u) * nloc) {
;             __builtin_amdgcn_fence(__ATOMIC_RELEASE, "agent");
;             asm volatile("s_waitcnt vmcnt(0)" ::: "memory");
;             const unsigned og = xb_add(&bar[XB_TOP], 1u);
;             const unsigned tg = og / nx;
;             if (og + 1u == (tg + 1u) * nx) xb_add(&bar[XB_TOPGEN], 1u);
;             else XB_SPIN(xb_ld(&bar[XB_TOPGEN]) == tg, bar);
;             __builtin_amdgcn_fence(__ATOMIC_ACQUIRE, "agent");
;             asm volatile("s_waitcnt vmcnt(0)" ::: "memory");
;         } else {
;             XB_SPIN(xb_ld(&bar[XB_TOPGEN]) == gen, bar);
.LBB0_218:
	s_or_b64 exec, exec, s[4:5]
	buffer_inv sc1
	v_cvt_f32_u32_e32 v5, v3
	s_waitcnt vmcnt(0)
	v_readfirstlane_b32 s6, v4
	s_add_u32 s4, s86, 0x3500
	s_addc_u32 s5, s87, 0
	v_rcp_iflag_f32_e32 v5, v5
	v_add_u32_e32 v6, s6, v2
	v_mul_f32_e32 v4, 0x4f7ffffe, v5
	v_cvt_u32_f32_e32 v4, v4
	v_sub_u32_e32 v5, 0, v3
	v_mul_lo_u32 v2, v5, v4
	v_mul_hi_u32 v2, v4, v2
	v_add_u32_e32 v2, v4, v2
	v_mul_hi_u32 v2, v6, v2
	v_mul_lo_u32 v4, v2, v3
	v_sub_u32_e32 v4, v6, v4
	v_add_u32_e32 v5, 1, v2
	v_cmp_ge_u32_e32 vcc, v4, v3
	s_nop 1
	v_cndmask_b32_e32 v2, v2, v5, vcc
	v_sub_u32_e32 v5, v4, v3
	v_cndmask_b32_e32 v4, v4, v5, vcc
	v_add_u32_e32 v5, 1, v2
	v_cmp_ge_u32_e32 vcc, v4, v3
	v_add_u32_e32 v4, 1, v6
	s_nop 0
	v_cndmask_b32_e32 v2, v2, v5, vcc
	v_mul_lo_u32 v5, v3, v2
	v_add_u32_e32 v3, v5, v3
	v_cmp_ne_u32_e32 vcc, v4, v3
	s_and_saveexec_b64 s[6:7], vcc
	s_xor_b64 s[6:7], exec, s[6:7]
	s_cbranch_execz .LBB0_232
	s_waitcnt lgkmcnt(0)
	v_mov_b32_e32 v1, 0
	global_load_dword v3, v1, s[4:5] sc1
	s_waitcnt vmcnt(0)
	v_cmp_eq_u32_e32 vcc, v3, v2
	s_and_saveexec_b64 s[8:9], vcc
	s_cbranch_execz .LBB0_231
	s_mov_b32 s20, 1
	s_mov_b64 s[10:11], 0
	s_branch .LBB0_222

; __device__ __forceinline__ unsigned xb_ld(unsigned* p)              { return __hip_atomic_load(p, __ATOMIC_RELAXED, __HIP_MEMORY_SCOPE_AGENT); }
; #define XB_SPIN(cond, bar) do { unsigned _sp = 0; while (cond) { __builtin_amdgcn_s_sleep(1); \
;     if ((++_sp & 255u) == 0u) { if (xb_ld(&(bar)[XB_TMO])) break; if (_sp > XB_SPIN_CAP) { atomicAdd(&(bar)[XB_TMO], 1u); break; } } } } while (0)
; __device__ __forceinline__ void xcd_barrier(const XcdBarrier& b) {
;     ...
;             XB_SPIN(xb_ld(&bar[XB_TOPGEN]) == gen, bar);
;             __builtin_amdgcn_fence(__ATOMIC_ACQUIRE, "agent");
;             asm volatile("s_waitcnt vmcnt(0)" ::: "memory");
.LBB0_231:
	s_or_b64 exec, exec, s[8:9]
	s_waitcnt vmcnt(0)
	s_waitcnt vmcnt(0)

; __device__ __forceinline__ unsigned xb_ld(unsigned* p)              { return __hip_atomic_load(p, __ATOMIC_RELAXED, __HIP_MEMORY_SCOPE_AGENT); }
; #define XB_SPIN(cond, bar) do { unsigned _sp = 0; while (cond) { __builtin_amdgcn_s_sleep(1); \
;     if ((++_sp & 255u) == 0u) { if (xb_ld(&(bar)[XB_TMO])) break; if (_sp > XB_SPIN_CAP) { atomicAdd(&(bar)[XB_TMO], 1u); break; } } } } while (0)
; __device__ __forceinline__ void xcd_barrier(const XcdBarrier& b) {
;     ...
;             else XB_SPIN(xb_ld(&bar[XB_TOPGEN]) == tg, bar);
;             __builtin_amdgcn_fence(__ATOMIC_ACQUIRE, "agent");
;             asm volatile("s_waitcnt vmcnt(0)" ::: "memory");
.LBB0_249:
	s_or_b64 exec, exec, s[2:3]
	s_waitcnt vmcnt(0)
	s_waitcnt vmcnt(0)
